# P0 transposes: three tiles of loads in flight per block (was one)
# speedup vs baseline: 1.0110x; 1.0004x over previous
.Ltr_j0d:
	s_sub_u32 s4, s4, 0x980
	s_cmpk_ge_u32 s4, 0x2300
	s_cbranch_scc1 .Ltr_done
	s_mov_b32 s19, s4
	s_mov_b32 s5, s19

.Ltr_p0_end:
	s_mov_b64 s[16:17], s[14:15]
	s_mov_b32 s26, s6
	s_mov_b32 s27, s13
	v_mad_u32_u24 v4, v78, s12, v1
	v_mad_u32_u24 v5, v79, s12, v1
	v_mad_u32_u24 v6, v80, s12, v1
	v_mad_u32_u24 v7, v81, s12, v1
	global_load_dwordx4 v[16:19], v4, s[10:11]
	global_load_dwordx4 v[20:23], v5, s[10:11]
	global_load_dwordx4 v[24:27], v6, s[10:11]
	global_load_dwordx4 v[28:31], v7, s[10:11]
	s_add_u32 s18, s19, s3
	s_cmpk_lt_u32 s18, 0x2300
	s_cselect_b32 s19, s18, s19
	s_mov_b32 s5, s19

.Ltr_p1_end:
	s_mov_b64 s[40:41], s[14:15]
	s_mov_b32 s42, s6
	s_mov_b32 s43, s13
	v_mad_u32_u24 v4, v78, s12, v1
	v_mad_u32_u24 v5, v79, s12, v1
	v_mad_u32_u24 v6, v80, s12, v1
	v_mad_u32_u24 v7, v81, s12, v1
	global_load_dwordx4 v[32:35], v4, s[10:11]
	global_load_dwordx4 v[36:39], v5, s[10:11]
	global_load_dwordx4 v[40:43], v6, s[10:11]
	global_load_dwordx4 v[44:47], v7, s[10:11]
	s_add_u32 s18, s19, s3
	s_cmpk_lt_u32 s18, 0x2300
	s_cselect_b32 s19, s18, s19
	s_mov_b32 s5, s19

.Ltr_p2_end:
	s_mov_b64 s[44:45], s[14:15]
	s_mov_b32 s46, s6
	s_mov_b32 s47, s13
	v_mad_u32_u24 v4, v78, s12, v1
	v_mad_u32_u24 v5, v79, s12, v1
	v_mad_u32_u24 v6, v80, s12, v1
	v_mad_u32_u24 v7, v81, s12, v1
	global_load_dwordx4 v[84:87], v4, s[10:11]
	global_load_dwordx4 v[88:91], v5, s[10:11]
	global_load_dwordx4 v[92:95], v6, s[10:11]
	global_load_dwordx4 v[96:99], v7, s[10:11]
	s_add_u32 s18, s19, s3
	s_cmpk_lt_u32 s18, 0x2300
	s_cselect_b32 s19, s18, s19
	s_mov_b32 s5, s19

.Ltr_q0_end:
	s_mov_b64 s[48:49], s[14:15]
	s_mov_b32 s50, s6
	s_mov_b32 s51, s13
	v_mad_u32_u24 v4, v78, s12, v1
	v_mad_u32_u24 v5, v79, s12, v1
	v_mad_u32_u24 v6, v80, s12, v1
	v_mad_u32_u24 v7, v81, s12, v1
	global_load_dwordx4 v[100:103], v4, s[10:11]
	global_load_dwordx4 v[104:107], v5, s[10:11]
	global_load_dwordx4 v[108:111], v6, s[10:11]
	global_load_dwordx4 v[112:115], v7, s[10:11]
	s_waitcnt vmcnt(12)
	ds_write2_b32 v8, v16, v17 offset1:1
	ds_write2_b32 v8, v18, v19 offset0:2 offset1:3
	ds_write2_b32 v9, v20, v21 offset1:1
	ds_write2_b32 v9, v22, v23 offset0:2 offset1:3
	ds_write2_b32 v10, v24, v25 offset1:1
	ds_write2_b32 v10, v26, v27 offset0:2 offset1:3
	ds_write2_b32 v11, v28, v29 offset1:1
	ds_write2_b32 v11, v30, v31 offset0:2 offset1:3
	v_and_b32_e32 v82, s27, v2
	v_xor_b32_e32 v82, s26, v82
	v_lshl_add_u32 v82, v82, 7, v14
	v_add_u32_e32 v83, 0x20000, v82
	s_waitcnt lgkmcnt(0)
	s_barrier
	ds_read2_b32 v[48:49], v12 offset1:65
	ds_read2_b32 v[50:51], v12 offset0:130 offset1:195
	ds_read2_b32 v[52:53], v13 offset1:65
	ds_read2_b32 v[54:55], v13 offset0:130 offset1:195
	ds_read2_b32 v[56:57], v12 offset0:32 offset1:97
	ds_read2_b32 v[58:59], v12 offset0:162 offset1:227
	ds_read2_b32 v[60:61], v13 offset0:32 offset1:97
	ds_read2_b32 v[62:63], v13 offset0:162 offset1:227
	s_waitcnt lgkmcnt(4)
	v_cvt_pk_bf16_f32 v64, v48, v49
	v_cvt_pk_bf16_f32 v65, v50, v51
	v_cvt_pk_bf16_f32 v66, v52, v53
	v_cvt_pk_bf16_f32 v67, v54, v55
	s_waitcnt lgkmcnt(0)
	v_cvt_pk_bf16_f32 v68, v56, v57
	v_cvt_pk_bf16_f32 v69, v58, v59
	v_cvt_pk_bf16_f32 v70, v60, v61
	v_cvt_pk_bf16_f32 v71, v62, v63
	global_store_dwordx4 v82, v[64:67], s[16:17]
	global_store_dwordx4 v83, v[68:71], s[16:17]
	s_mov_b64 s[16:17], s[40:41]
	s_mov_b32 s26, s42
	s_mov_b32 s27, s43
	s_mov_b64 s[40:41], s[44:45]
	s_mov_b32 s42, s46
	s_mov_b32 s43, s47
	s_mov_b64 s[44:45], s[48:49]
	s_mov_b32 s46, s50
	s_mov_b32 s47, s51
	s_add_u32 s4, s4, s3
	s_cmpk_lt_u32 s4, 0x2300
	s_cbranch_scc0 .Ltr_drain
	s_add_u32 s18, s19, s3
	s_cmpk_lt_u32 s18, 0x2300
	s_cselect_b32 s19, s18, s19
	s_mov_b32 s5, s19

.Ltr_q1_end:
	s_mov_b64 s[48:49], s[14:15]
	s_mov_b32 s50, s6
	s_mov_b32 s51, s13
	v_mad_u32_u24 v4, v78, s12, v1
	v_mad_u32_u24 v5, v79, s12, v1
	v_mad_u32_u24 v6, v80, s12, v1
	v_mad_u32_u24 v7, v81, s12, v1
	global_load_dwordx4 v[16:19], v4, s[10:11]
	global_load_dwordx4 v[20:23], v5, s[10:11]
	global_load_dwordx4 v[24:27], v6, s[10:11]
	global_load_dwordx4 v[28:31], v7, s[10:11]
	s_waitcnt vmcnt(14)
	ds_write2_b32 v72, v32, v33 offset1:1
	ds_write2_b32 v72, v34, v35 offset0:2 offset1:3
	ds_write2_b32 v73, v36, v37 offset1:1
	ds_write2_b32 v73, v38, v39 offset0:2 offset1:3
	ds_write2_b32 v74, v40, v41 offset1:1
	ds_write2_b32 v74, v42, v43 offset0:2 offset1:3
	ds_write2_b32 v75, v44, v45 offset1:1
	ds_write2_b32 v75, v46, v47 offset0:2 offset1:3
	v_and_b32_e32 v82, s27, v2
	v_xor_b32_e32 v82, s26, v82
	v_lshl_add_u32 v82, v82, 7, v14
	v_add_u32_e32 v83, 0x20000, v82
	s_waitcnt lgkmcnt(0)
	s_barrier
	ds_read2_b32 v[48:49], v76 offset1:65
	ds_read2_b32 v[50:51], v76 offset0:130 offset1:195
	ds_read2_b32 v[52:53], v77 offset1:65
	ds_read2_b32 v[54:55], v77 offset0:130 offset1:195
	ds_read2_b32 v[56:57], v76 offset0:32 offset1:97
	ds_read2_b32 v[58:59], v76 offset0:162 offset1:227
	ds_read2_b32 v[60:61], v77 offset0:32 offset1:97
	ds_read2_b32 v[62:63], v77 offset0:162 offset1:227
	s_waitcnt lgkmcnt(4)
	v_cvt_pk_bf16_f32 v64, v48, v49
	v_cvt_pk_bf16_f32 v65, v50, v51
	v_cvt_pk_bf16_f32 v66, v52, v53
	v_cvt_pk_bf16_f32 v67, v54, v55
	s_waitcnt lgkmcnt(0)
	v_cvt_pk_bf16_f32 v68, v56, v57
	v_cvt_pk_bf16_f32 v69, v58, v59
	v_cvt_pk_bf16_f32 v70, v60, v61
	v_cvt_pk_bf16_f32 v71, v62, v63
	global_store_dwordx4 v82, v[64:67], s[16:17]
	global_store_dwordx4 v83, v[68:71], s[16:17]
	s_mov_b64 s[16:17], s[40:41]
	s_mov_b32 s26, s42
	s_mov_b32 s27, s43
	s_mov_b64 s[40:41], s[44:45]
	s_mov_b32 s42, s46
	s_mov_b32 s43, s47
	s_mov_b64 s[44:45], s[48:49]
	s_mov_b32 s46, s50
	s_mov_b32 s47, s51
	s_add_u32 s4, s4, s3
	s_cmpk_lt_u32 s4, 0x2300
	s_cbranch_scc0 .Ltr_drain
	s_add_u32 s18, s19, s3
	s_cmpk_lt_u32 s18, 0x2300
	s_cselect_b32 s19, s18, s19
	s_mov_b32 s5, s19

.Ltr_q2_end:
	s_mov_b64 s[48:49], s[14:15]
	s_mov_b32 s50, s6
	s_mov_b32 s51, s13
	v_mad_u32_u24 v4, v78, s12, v1
	v_mad_u32_u24 v5, v79, s12, v1
	v_mad_u32_u24 v6, v80, s12, v1
	v_mad_u32_u24 v7, v81, s12, v1
	global_load_dwordx4 v[32:35], v4, s[10:11]
	global_load_dwordx4 v[36:39], v5, s[10:11]
	global_load_dwordx4 v[40:43], v6, s[10:11]
	global_load_dwordx4 v[44:47], v7, s[10:11]
	s_waitcnt vmcnt(16)
	ds_write2_b32 v8, v84, v85 offset1:1
	ds_write2_b32 v8, v86, v87 offset0:2 offset1:3
	ds_write2_b32 v9, v88, v89 offset1:1
	ds_write2_b32 v9, v90, v91 offset0:2 offset1:3
	ds_write2_b32 v10, v92, v93 offset1:1
	ds_write2_b32 v10, v94, v95 offset0:2 offset1:3
	ds_write2_b32 v11, v96, v97 offset1:1
	ds_write2_b32 v11, v98, v99 offset0:2 offset1:3
	v_and_b32_e32 v82, s27, v2
	v_xor_b32_e32 v82, s26, v82
	v_lshl_add_u32 v82, v82, 7, v14
	v_add_u32_e32 v83, 0x20000, v82
	s_waitcnt lgkmcnt(0)
	s_barrier
	ds_read2_b32 v[48:49], v12 offset1:65
	ds_read2_b32 v[50:51], v12 offset0:130 offset1:195
	ds_read2_b32 v[52:53], v13 offset1:65
	ds_read2_b32 v[54:55], v13 offset0:130 offset1:195
	ds_read2_b32 v[56:57], v12 offset0:32 offset1:97
	ds_read2_b32 v[58:59], v12 offset0:162 offset1:227
	ds_read2_b32 v[60:61], v13 offset0:32 offset1:97
	ds_read2_b32 v[62:63], v13 offset0:162 offset1:227
	s_waitcnt lgkmcnt(4)
	v_cvt_pk_bf16_f32 v64, v48, v49
	v_cvt_pk_bf16_f32 v65, v50, v51
	v_cvt_pk_bf16_f32 v66, v52, v53
	v_cvt_pk_bf16_f32 v67, v54, v55
	s_waitcnt lgkmcnt(0)
	v_cvt_pk_bf16_f32 v68, v56, v57
	v_cvt_pk_bf16_f32 v69, v58, v59
	v_cvt_pk_bf16_f32 v70, v60, v61
	v_cvt_pk_bf16_f32 v71, v62, v63
	global_store_dwordx4 v82, v[64:67], s[16:17]
	global_store_dwordx4 v83, v[68:71], s[16:17]
	s_mov_b64 s[16:17], s[40:41]
	s_mov_b32 s26, s42
	s_mov_b32 s27, s43
	s_mov_b64 s[40:41], s[44:45]
	s_mov_b32 s42, s46
	s_mov_b32 s43, s47
	s_mov_b64 s[44:45], s[48:49]
	s_mov_b32 s46, s50
	s_mov_b32 s47, s51
	s_add_u32 s4, s4, s3
	s_cmpk_lt_u32 s4, 0x2300
	s_cbranch_scc0 .Ltr_drain
	s_add_u32 s18, s19, s3
	s_cmpk_lt_u32 s18, 0x2300
	s_cselect_b32 s19, s18, s19
	s_mov_b32 s5, s19

.Ltr_q3_end:
	s_mov_b64 s[48:49], s[14:15]
	s_mov_b32 s50, s6
	s_mov_b32 s51, s13
	v_mad_u32_u24 v4, v78, s12, v1
	v_mad_u32_u24 v5, v79, s12, v1
	v_mad_u32_u24 v6, v80, s12, v1
	v_mad_u32_u24 v7, v81, s12, v1
	global_load_dwordx4 v[84:87], v4, s[10:11]
	global_load_dwordx4 v[88:91], v5, s[10:11]
	global_load_dwordx4 v[92:95], v6, s[10:11]
	global_load_dwordx4 v[96:99], v7, s[10:11]
	s_waitcnt vmcnt(18)
	ds_write2_b32 v72, v100, v101 offset1:1
	ds_write2_b32 v72, v102, v103 offset0:2 offset1:3
	ds_write2_b32 v73, v104, v105 offset1:1
	ds_write2_b32 v73, v106, v107 offset0:2 offset1:3
	ds_write2_b32 v74, v108, v109 offset1:1
	ds_write2_b32 v74, v110, v111 offset0:2 offset1:3
	ds_write2_b32 v75, v112, v113 offset1:1
	ds_write2_b32 v75, v114, v115 offset0:2 offset1:3
	v_and_b32_e32 v82, s27, v2
	v_xor_b32_e32 v82, s26, v82
	v_lshl_add_u32 v82, v82, 7, v14
	v_add_u32_e32 v83, 0x20000, v82
	s_waitcnt lgkmcnt(0)
	s_barrier
	ds_read2_b32 v[48:49], v76 offset1:65
	ds_read2_b32 v[50:51], v76 offset0:130 offset1:195
	ds_read2_b32 v[52:53], v77 offset1:65
	ds_read2_b32 v[54:55], v77 offset0:130 offset1:195
	ds_read2_b32 v[56:57], v76 offset0:32 offset1:97
	ds_read2_b32 v[58:59], v76 offset0:162 offset1:227
	ds_read2_b32 v[60:61], v77 offset0:32 offset1:97
	ds_read2_b32 v[62:63], v77 offset0:162 offset1:227
	s_waitcnt lgkmcnt(4)
	v_cvt_pk_bf16_f32 v64, v48, v49
	v_cvt_pk_bf16_f32 v65, v50, v51
	v_cvt_pk_bf16_f32 v66, v52, v53
	v_cvt_pk_bf16_f32 v67, v54, v55
	s_waitcnt lgkmcnt(0)
	v_cvt_pk_bf16_f32 v68, v56, v57
	v_cvt_pk_bf16_f32 v69, v58, v59
	v_cvt_pk_bf16_f32 v70, v60, v61
	v_cvt_pk_bf16_f32 v71, v62, v63
	global_store_dwordx4 v82, v[64:67], s[16:17]
	global_store_dwordx4 v83, v[68:71], s[16:17]
	s_mov_b64 s[16:17], s[40:41]
	s_mov_b32 s26, s42
	s_mov_b32 s27, s43
	s_mov_b64 s[40:41], s[44:45]
	s_mov_b32 s42, s46
	s_mov_b32 s43, s47
	s_mov_b64 s[44:45], s[48:49]
	s_mov_b32 s46, s50
	s_mov_b32 s47, s51
	s_add_u32 s4, s4, s3
	s_cmpk_lt_u32 s4, 0x2300
	s_cbranch_scc0 .Ltr_drain
.Ltr_loop:
	s_add_u32 s18, s19, s3
	s_cmpk_lt_u32 s18, 0x2300
	s_cselect_b32 s19, s18, s19
	s_mov_b32 s5, s19

.Ltr_l0_end:
	s_mov_b64 s[48:49], s[14:15]
	s_mov_b32 s50, s6
	s_mov_b32 s51, s13
	v_mad_u32_u24 v4, v78, s12, v1
	v_mad_u32_u24 v5, v79, s12, v1
	v_mad_u32_u24 v6, v80, s12, v1
	v_mad_u32_u24 v7, v81, s12, v1
	global_load_dwordx4 v[100:103], v4, s[10:11]
	global_load_dwordx4 v[104:107], v5, s[10:11]
	global_load_dwordx4 v[108:111], v6, s[10:11]
	global_load_dwordx4 v[112:115], v7, s[10:11]
	s_waitcnt vmcnt(18)
	ds_write2_b32 v8, v16, v17 offset1:1
	ds_write2_b32 v8, v18, v19 offset0:2 offset1:3
	ds_write2_b32 v9, v20, v21 offset1:1
	ds_write2_b32 v9, v22, v23 offset0:2 offset1:3
	ds_write2_b32 v10, v24, v25 offset1:1
	ds_write2_b32 v10, v26, v27 offset0:2 offset1:3
	ds_write2_b32 v11, v28, v29 offset1:1
	ds_write2_b32 v11, v30, v31 offset0:2 offset1:3
	v_and_b32_e32 v82, s27, v2
	v_xor_b32_e32 v82, s26, v82
	v_lshl_add_u32 v82, v82, 7, v14
	v_add_u32_e32 v83, 0x20000, v82
	s_waitcnt lgkmcnt(0)
	s_barrier
	ds_read2_b32 v[48:49], v12 offset1:65
	ds_read2_b32 v[50:51], v12 offset0:130 offset1:195
	ds_read2_b32 v[52:53], v13 offset1:65
	ds_read2_b32 v[54:55], v13 offset0:130 offset1:195
	ds_read2_b32 v[56:57], v12 offset0:32 offset1:97
	ds_read2_b32 v[58:59], v12 offset0:162 offset1:227
	ds_read2_b32 v[60:61], v13 offset0:32 offset1:97
	ds_read2_b32 v[62:63], v13 offset0:162 offset1:227
	s_waitcnt lgkmcnt(4)
	v_cvt_pk_bf16_f32 v64, v48, v49
	v_cvt_pk_bf16_f32 v65, v50, v51
	v_cvt_pk_bf16_f32 v66, v52, v53
	v_cvt_pk_bf16_f32 v67, v54, v55
	s_waitcnt lgkmcnt(0)
	v_cvt_pk_bf16_f32 v68, v56, v57
	v_cvt_pk_bf16_f32 v69, v58, v59
	v_cvt_pk_bf16_f32 v70, v60, v61
	v_cvt_pk_bf16_f32 v71, v62, v63
	global_store_dwordx4 v82, v[64:67], s[16:17]
	global_store_dwordx4 v83, v[68:71], s[16:17]
	s_mov_b64 s[16:17], s[40:41]
	s_mov_b32 s26, s42
	s_mov_b32 s27, s43
	s_mov_b64 s[40:41], s[44:45]
	s_mov_b32 s42, s46
	s_mov_b32 s43, s47
	s_mov_b64 s[44:45], s[48:49]
	s_mov_b32 s46, s50
	s_mov_b32 s47, s51
	s_add_u32 s4, s4, s3
	s_cmpk_lt_u32 s4, 0x2300
	s_cbranch_scc0 .Ltr_drain
	s_add_u32 s18, s19, s3
	s_cmpk_lt_u32 s18, 0x2300
	s_cselect_b32 s19, s18, s19
	s_mov_b32 s5, s19

.Ltr_l1_end:
	s_mov_b64 s[48:49], s[14:15]
	s_mov_b32 s50, s6
	s_mov_b32 s51, s13
	v_mad_u32_u24 v4, v78, s12, v1
	v_mad_u32_u24 v5, v79, s12, v1
	v_mad_u32_u24 v6, v80, s12, v1
	v_mad_u32_u24 v7, v81, s12, v1
	global_load_dwordx4 v[16:19], v4, s[10:11]
	global_load_dwordx4 v[20:23], v5, s[10:11]
	global_load_dwordx4 v[24:27], v6, s[10:11]
	global_load_dwordx4 v[28:31], v7, s[10:11]
	s_waitcnt vmcnt(18)
	ds_write2_b32 v72, v32, v33 offset1:1
	ds_write2_b32 v72, v34, v35 offset0:2 offset1:3
	ds_write2_b32 v73, v36, v37 offset1:1
	ds_write2_b32 v73, v38, v39 offset0:2 offset1:3
	ds_write2_b32 v74, v40, v41 offset1:1
	ds_write2_b32 v74, v42, v43 offset0:2 offset1:3
	ds_write2_b32 v75, v44, v45 offset1:1
	ds_write2_b32 v75, v46, v47 offset0:2 offset1:3
	v_and_b32_e32 v82, s27, v2
	v_xor_b32_e32 v82, s26, v82
	v_lshl_add_u32 v82, v82, 7, v14
	v_add_u32_e32 v83, 0x20000, v82
	s_waitcnt lgkmcnt(0)
	s_barrier
	ds_read2_b32 v[48:49], v76 offset1:65
	ds_read2_b32 v[50:51], v76 offset0:130 offset1:195
	ds_read2_b32 v[52:53], v77 offset1:65
	ds_read2_b32 v[54:55], v77 offset0:130 offset1:195
	ds_read2_b32 v[56:57], v76 offset0:32 offset1:97
	ds_read2_b32 v[58:59], v76 offset0:162 offset1:227
	ds_read2_b32 v[60:61], v77 offset0:32 offset1:97
	ds_read2_b32 v[62:63], v77 offset0:162 offset1:227
	s_waitcnt lgkmcnt(4)
	v_cvt_pk_bf16_f32 v64, v48, v49
	v_cvt_pk_bf16_f32 v65, v50, v51
	v_cvt_pk_bf16_f32 v66, v52, v53
	v_cvt_pk_bf16_f32 v67, v54, v55
	s_waitcnt lgkmcnt(0)
	v_cvt_pk_bf16_f32 v68, v56, v57
	v_cvt_pk_bf16_f32 v69, v58, v59
	v_cvt_pk_bf16_f32 v70, v60, v61
	v_cvt_pk_bf16_f32 v71, v62, v63
	global_store_dwordx4 v82, v[64:67], s[16:17]
	global_store_dwordx4 v83, v[68:71], s[16:17]
	s_mov_b64 s[16:17], s[40:41]
	s_mov_b32 s26, s42
	s_mov_b32 s27, s43
	s_mov_b64 s[40:41], s[44:45]
	s_mov_b32 s42, s46
	s_mov_b32 s43, s47
	s_mov_b64 s[44:45], s[48:49]
	s_mov_b32 s46, s50
	s_mov_b32 s47, s51
	s_add_u32 s4, s4, s3
	s_cmpk_lt_u32 s4, 0x2300
	s_cbranch_scc0 .Ltr_drain
	s_add_u32 s18, s19, s3
	s_cmpk_lt_u32 s18, 0x2300
	s_cselect_b32 s19, s18, s19
	s_mov_b32 s5, s19

.Ltr_l2_end:
	s_mov_b64 s[48:49], s[14:15]
	s_mov_b32 s50, s6
	s_mov_b32 s51, s13
	v_mad_u32_u24 v4, v78, s12, v1
	v_mad_u32_u24 v5, v79, s12, v1
	v_mad_u32_u24 v6, v80, s12, v1
	v_mad_u32_u24 v7, v81, s12, v1
	global_load_dwordx4 v[32:35], v4, s[10:11]
	global_load_dwordx4 v[36:39], v5, s[10:11]
	global_load_dwordx4 v[40:43], v6, s[10:11]
	global_load_dwordx4 v[44:47], v7, s[10:11]
	s_waitcnt vmcnt(18)
	ds_write2_b32 v8, v84, v85 offset1:1
	ds_write2_b32 v8, v86, v87 offset0:2 offset1:3
	ds_write2_b32 v9, v88, v89 offset1:1
	ds_write2_b32 v9, v90, v91 offset0:2 offset1:3
	ds_write2_b32 v10, v92, v93 offset1:1
	ds_write2_b32 v10, v94, v95 offset0:2 offset1:3
	ds_write2_b32 v11, v96, v97 offset1:1
	ds_write2_b32 v11, v98, v99 offset0:2 offset1:3
	v_and_b32_e32 v82, s27, v2
	v_xor_b32_e32 v82, s26, v82
	v_lshl_add_u32 v82, v82, 7, v14
	v_add_u32_e32 v83, 0x20000, v82
	s_waitcnt lgkmcnt(0)
	s_barrier
	ds_read2_b32 v[48:49], v12 offset1:65
	ds_read2_b32 v[50:51], v12 offset0:130 offset1:195
	ds_read2_b32 v[52:53], v13 offset1:65
	ds_read2_b32 v[54:55], v13 offset0:130 offset1:195
	ds_read2_b32 v[56:57], v12 offset0:32 offset1:97
	ds_read2_b32 v[58:59], v12 offset0:162 offset1:227
	ds_read2_b32 v[60:61], v13 offset0:32 offset1:97
	ds_read2_b32 v[62:63], v13 offset0:162 offset1:227
	s_waitcnt lgkmcnt(4)
	v_cvt_pk_bf16_f32 v64, v48, v49
	v_cvt_pk_bf16_f32 v65, v50, v51
	v_cvt_pk_bf16_f32 v66, v52, v53
	v_cvt_pk_bf16_f32 v67, v54, v55
	s_waitcnt lgkmcnt(0)
	v_cvt_pk_bf16_f32 v68, v56, v57
	v_cvt_pk_bf16_f32 v69, v58, v59
	v_cvt_pk_bf16_f32 v70, v60, v61
	v_cvt_pk_bf16_f32 v71, v62, v63
	global_store_dwordx4 v82, v[64:67], s[16:17]
	global_store_dwordx4 v83, v[68:71], s[16:17]
	s_mov_b64 s[16:17], s[40:41]
	s_mov_b32 s26, s42
	s_mov_b32 s27, s43
	s_mov_b64 s[40:41], s[44:45]
	s_mov_b32 s42, s46
	s_mov_b32 s43, s47
	s_mov_b64 s[44:45], s[48:49]
	s_mov_b32 s46, s50
	s_mov_b32 s47, s51
	s_add_u32 s4, s4, s3
	s_cmpk_lt_u32 s4, 0x2300
	s_cbranch_scc0 .Ltr_drain
	s_add_u32 s18, s19, s3
	s_cmpk_lt_u32 s18, 0x2300
	s_cselect_b32 s19, s18, s19
	s_mov_b32 s5, s19

.Ltr_l3_end:
	s_mov_b64 s[48:49], s[14:15]
	s_mov_b32 s50, s6
	s_mov_b32 s51, s13
	v_mad_u32_u24 v4, v78, s12, v1
	v_mad_u32_u24 v5, v79, s12, v1
	v_mad_u32_u24 v6, v80, s12, v1
	v_mad_u32_u24 v7, v81, s12, v1
	global_load_dwordx4 v[84:87], v4, s[10:11]
	global_load_dwordx4 v[88:91], v5, s[10:11]
	global_load_dwordx4 v[92:95], v6, s[10:11]
	global_load_dwordx4 v[96:99], v7, s[10:11]
	s_waitcnt vmcnt(18)
	ds_write2_b32 v72, v100, v101 offset1:1
	ds_write2_b32 v72, v102, v103 offset0:2 offset1:3
	ds_write2_b32 v73, v104, v105 offset1:1
	ds_write2_b32 v73, v106, v107 offset0:2 offset1:3
	ds_write2_b32 v74, v108, v109 offset1:1
	ds_write2_b32 v74, v110, v111 offset0:2 offset1:3
	ds_write2_b32 v75, v112, v113 offset1:1
	ds_write2_b32 v75, v114, v115 offset0:2 offset1:3
	v_and_b32_e32 v82, s27, v2
	v_xor_b32_e32 v82, s26, v82
	v_lshl_add_u32 v82, v82, 7, v14
	v_add_u32_e32 v83, 0x20000, v82
	s_waitcnt lgkmcnt(0)
	s_barrier
	ds_read2_b32 v[48:49], v76 offset1:65
	ds_read2_b32 v[50:51], v76 offset0:130 offset1:195
	ds_read2_b32 v[52:53], v77 offset1:65
	ds_read2_b32 v[54:55], v77 offset0:130 offset1:195
	ds_read2_b32 v[56:57], v76 offset0:32 offset1:97
	ds_read2_b32 v[58:59], v76 offset0:162 offset1:227
	ds_read2_b32 v[60:61], v77 offset0:32 offset1:97
	ds_read2_b32 v[62:63], v77 offset0:162 offset1:227
	s_waitcnt lgkmcnt(4)
	v_cvt_pk_bf16_f32 v64, v48, v49
	v_cvt_pk_bf16_f32 v65, v50, v51
	v_cvt_pk_bf16_f32 v66, v52, v53
	v_cvt_pk_bf16_f32 v67, v54, v55
	s_waitcnt lgkmcnt(0)
	v_cvt_pk_bf16_f32 v68, v56, v57
	v_cvt_pk_bf16_f32 v69, v58, v59
	v_cvt_pk_bf16_f32 v70, v60, v61
	v_cvt_pk_bf16_f32 v71, v62, v63
	global_store_dwordx4 v82, v[64:67], s[16:17]
	global_store_dwordx4 v83, v[68:71], s[16:17]
	s_mov_b64 s[16:17], s[40:41]
	s_mov_b32 s26, s42
	s_mov_b32 s27, s43
	s_mov_b64 s[40:41], s[44:45]
	s_mov_b32 s42, s46
	s_mov_b32 s43, s47
	s_mov_b64 s[44:45], s[48:49]
	s_mov_b32 s46, s50
	s_mov_b32 s47, s51
	s_add_u32 s4, s4, s3
	s_cmpk_lt_u32 s4, 0x2300
	s_cbranch_scc0 .Ltr_drain
	s_branch .Ltr_loop
